# P3 epilogue: the four gate rows loaded up front into free registers (three load round trips per tile removed)
# baseline (speedup 1.0000x reference)
;     __device__ __forceinline__ void operator()(const f32x4 (&acc)[2][2][4][2], const pg8::Unit& u, int wr, int wc, int fr, int fq) const {
;         const bool isx = u.pm < (MX / 256);
;         const int mr = isx ? (u.pm >> 4) : 8;
;         const float* gate = modv + (size_t)mr * MODW + gslot * D;
;         const int lrow0 = (isx ? u.pm : u.pm - MX / 256) * 256 + wr * 64 + fr;
;         const float* src = isx ? Xx : Xc; float* dst = isx ? Yx : Yc;
;         const int grow0 = u.pm * 256 + wr * 64 + fr;
;         f32x2 stv[2][4];
; #pragma unroll
;         for (int ai = 0; ai < 2; ++ai)
; #pragma unroll
;             for (int m = 0; m < 4; ++m) stv[ai][m] = stats ? stats[grow0 + ai * 128 + m * 16] : (f32x2){0.f, 1.f};
; #pragma unroll
;         for (int bj = 0; bj < 2; ++bj)
; #pragma unroll
;             for (int n = 0; n < 2; ++n) {
;                 const int col = u.pn * 256 + bj * 128 + wc * 32 + n * 16 + 4 * fq;
;                 const f32x4 gv = *(const f32x4*)(gate + col) * gscale;
;                 f32x4 lgv = (f32x4){1.f, 1.f, 1.f, 1.f}, lbv = (f32x4){0.f, 0.f, 0.f, 0.f};
;                 if (stats) { lgv = *(const f32x4*)(lg + col); lbv = *(const f32x4*)(lb + col); }
;                 f32x4 xv[2][4];
; #pragma unroll
;                 for (int ai = 0; ai < 2; ++ai)
; #pragma unroll
;                     for (int m = 0; m < 4; ++m) xv[ai][m] = *(const f32x4*)(src + (size_t)(lrow0 + ai * 128 + m * 16) * D + col);
; #pragma unroll
;                 for (int ai = 0; ai < 2; ++ai)
; #pragma unroll
;                     for (int m = 0; m < 4; ++m) {
;                         const size_t off = (size_t)(lrow0 + ai * 128 + m * 16) * D + col;
;                         f32x4 x = xv[ai][m];
;                         if (stats) x = (x - stv[ai][m].x) * stv[ai][m].y * lgv + lbv;
;                         *(f32x4*)(dst + off) = ALPHA * x + gv * acc[ai][bj][m][n];
.LBB0_287:
	s_lshl_b32 s24, s33, 8
	s_add_i32 s25, s24, 0xffff8000
	s_and_b64 s[22:23], s[22:23], exec
	s_cselect_b32 s24, s24, s25
	s_lshl_b64 s[22:23], s[46:47], 2
	s_add_u32 s22, s92, s22
	s_addc_u32 s23, s93, s23
	v_lshl_or_b32 v160, s94, 8, v183
	s_add_u32 s22, s22, 0x4000
	v_ashrrev_i32_e32 v161, 31, v160
	s_addc_u32 s23, s23, 0
	v_lshlrev_b64 v[168:169], 2, v[160:161]
	v_lshl_add_u64 v[128:129], s[22:23], 0, v[168:169]
	global_load_dwordx4 v[128:131], v[128:129], off
	v_or_b32_e32 v242, 16, v160
	v_ashrrev_i32_e32 v243, 31, v242
	v_lshl_add_u64 v[242:243], v[242:243], 2, s[22:23]
	global_load_dwordx4 v[228:231], v[242:243], off
	v_or_b32_e32 v242, 0x80, v160
	v_ashrrev_i32_e32 v243, 31, v242
	v_lshl_add_u64 v[242:243], v[242:243], 2, s[22:23]
	global_load_dwordx4 v[232:235], v[242:243], off
	v_or_b32_e32 v242, 0x90, v160
	v_ashrrev_i32_e32 v243, 31, v242
	v_lshl_add_u64 v[242:243], v[242:243], 2, s[22:23]
	global_load_dwordx4 v[236:239], v[242:243], off
	v_add_u32_e32 v150, s24, v181
	v_ashrrev_i32_e32 v151, 31, v150
	v_lshlrev_b64 v[216:217], 13, v[150:151]
	s_mov_b64 s[24:25], 0x100000
	v_lshl_add_u64 v[224:225], v[216:217], 0, s[24:25]
	v_lshl_add_u64 v[226:227], v[216:217], 0, s[10:11]
	v_lshl_add_u64 v[170:171], v[216:217], 0, s[16:17]
	s_mov_b64 s[24:25], 0x160000
	v_lshl_add_u64 v[166:167], v[216:217], 0, s[24:25]
	s_and_b64 vcc, exec, s[2:3]
	s_mov_b32 s94, s84
	s_mov_b32 s33, s85
	s_waitcnt vmcnt(0)
	v_pk_mul_f32 v[162:163], v[130:131], 0.5 op_sel_hi:[1,0]
	v_or_b32_e32 v130, 16, v150
	v_ashrrev_i32_e32 v131, 31, v130
	v_lshlrev_b64 v[218:219], 13, v[130:131]
	v_or_b32_e32 v130, 32, v150
	v_pk_mul_f32 v[164:165], v[128:129], 0.5 op_sel_hi:[1,0]
	v_lshl_add_u64 v[128:129], s[44:45], 0, v[168:169]
	v_ashrrev_i32_e32 v131, 31, v130
	v_lshl_add_u64 v[144:145], v[128:129], 0, v[216:217]
	v_lshlrev_b64 v[220:221], 13, v[130:131]
	v_or_b32_e32 v130, 48, v150
	global_load_dwordx4 v[188:191], v[144:145], off
	v_lshl_add_u64 v[146:147], v[128:129], 0, v[218:219]
	v_ashrrev_i32_e32 v131, 31, v130
	global_load_dwordx4 v[192:195], v[146:147], off
	v_lshl_add_u64 v[148:149], v[128:129], 0, v[220:221]
	v_lshlrev_b64 v[222:223], 13, v[130:131]
	global_load_dwordx4 v[196:199], v[148:149], off
	v_lshl_add_u64 v[150:151], v[128:129], 0, v[222:223]
	global_load_dwordx4 v[200:203], v[150:151], off
	v_lshl_add_u64 v[152:153], v[128:129], 0, v[224:225]
	global_load_dwordx4 v[204:207], v[152:153], off
	v_lshl_add_u64 v[154:155], v[128:129], 0, v[226:227]
	global_load_dwordx4 v[208:211], v[154:155], off
	v_lshl_add_u64 v[156:157], v[128:129], 0, v[170:171]
	global_load_dwordx4 v[212:215], v[156:157], off
	v_lshl_add_u64 v[158:159], v[128:129], 0, v[166:167]
	global_load_dwordx4 v[128:131], v[158:159], off
	v_lshl_add_u64 v[168:169], s[42:43], 0, v[168:169]
	v_pk_mul_f32 v[126:127], v[126:127], v[162:163]
	v_pk_mul_f32 v[124:125], v[124:125], v[164:165]
	s_mov_b64 s[42:43], s[4:5]
	s_waitcnt vmcnt(0)
	v_pk_fma_f32 v[190:191], v[190:191], s[20:21], v[126:127] op_sel_hi:[1,0,1]
	v_pk_fma_f32 v[188:189], v[188:189], s[20:21], v[124:125] op_sel_hi:[1,0,1]
	v_lshl_add_u64 v[124:125], v[168:169], 0, v[216:217]
	global_store_dwordx4 v[124:125], v[188:191], off
	v_pk_mul_f32 v[126:127], v[194:195], s[20:21] op_sel_hi:[1,0]
	s_nop 0
	v_pk_mul_f32 v[188:189], v[192:193], s[20:21] op_sel_hi:[1,0]
	v_pk_fma_f32 v[190:191], v[122:123], v[162:163], v[126:127]
	v_pk_fma_f32 v[188:189], v[120:121], v[164:165], v[188:189]
	v_lshl_add_u64 v[120:121], v[168:169], 0, v[218:219]
	v_pk_mul_f32 v[122:123], v[198:199], s[20:21] op_sel_hi:[1,0]
	v_pk_mul_f32 v[126:127], v[196:197], s[20:21] op_sel_hi:[1,0]
	global_store_dwordx4 v[120:121], v[188:191], off
	s_nop 1
	v_pk_fma_f32 v[190:191], v[118:119], v[162:163], v[122:123]
	v_pk_fma_f32 v[188:189], v[116:117], v[164:165], v[126:127]
	v_lshl_add_u64 v[116:117], v[168:169], 0, v[220:221]
	v_pk_mul_f32 v[118:119], v[202:203], s[20:21] op_sel_hi:[1,0]
	v_pk_mul_f32 v[122:123], v[200:201], s[20:21] op_sel_hi:[1,0]
	global_store_dwordx4 v[116:117], v[188:191], off
	s_nop 1
	v_pk_fma_f32 v[190:191], v[114:115], v[162:163], v[118:119]
	v_pk_fma_f32 v[188:189], v[112:113], v[164:165], v[122:123]
	v_lshl_add_u64 v[112:113], v[168:169], 0, v[222:223]
	v_pk_mul_f32 v[114:115], v[206:207], s[20:21] op_sel_hi:[1,0]
	v_pk_mul_f32 v[118:119], v[204:205], s[20:21] op_sel_hi:[1,0]
	global_store_dwordx4 v[112:113], v[188:191], off
	s_nop 1
	v_pk_fma_f32 v[190:191], v[110:111], v[162:163], v[114:115]
	v_pk_fma_f32 v[188:189], v[108:109], v[164:165], v[118:119]
	v_lshl_add_u64 v[108:109], v[168:169], 0, v[224:225]
	v_pk_mul_f32 v[110:111], v[210:211], s[20:21] op_sel_hi:[1,0]
	v_pk_mul_f32 v[114:115], v[208:209], s[20:21] op_sel_hi:[1,0]
	global_store_dwordx4 v[108:109], v[188:191], off
	s_nop 1
	v_pk_fma_f32 v[190:191], v[106:107], v[162:163], v[110:111]
	v_pk_fma_f32 v[188:189], v[104:105], v[164:165], v[114:115]
	v_lshl_add_u64 v[104:105], v[168:169], 0, v[226:227]
	v_pk_mul_f32 v[106:107], v[214:215], s[20:21] op_sel_hi:[1,0]
	global_store_dwordx4 v[104:105], v[188:191], off
	v_pk_mul_f32 v[110:111], v[212:213], s[20:21] op_sel_hi:[1,0]
	s_nop 0
	v_pk_fma_f32 v[190:191], v[102:103], v[162:163], v[106:107]
	v_pk_mul_f32 v[102:103], v[130:131], s[20:21] op_sel_hi:[1,0]
	v_pk_mul_f32 v[106:107], v[128:129], s[20:21] op_sel_hi:[1,0]
	v_pk_fma_f32 v[128:129], v[82:83], v[162:163], v[102:103]
	v_or_b32_e32 v82, 16, v160
	v_pk_fma_f32 v[188:189], v[100:101], v[164:165], v[110:111]
	v_lshl_add_u64 v[100:101], v[168:169], 0, v[170:171]
	v_pk_fma_f32 v[126:127], v[80:81], v[164:165], v[106:107]
	v_lshl_add_u64 v[80:81], v[168:169], 0, v[166:167]
	v_ashrrev_i32_e32 v83, 31, v82
	global_store_dwordx4 v[100:101], v[188:191], off
	global_store_dwordx4 v[80:81], v[126:129], off
	v_lshl_add_u64 v[82:83], v[82:83], 2, s[22:23]
	s_nop 0
	s_nop 0
	v_pk_mul_f32 v[82:83], v[230:231], 0.5 op_sel_hi:[1,0]
	v_pk_mul_f32 v[102:103], v[228:229], 0.5 op_sel_hi:[1,0]
	global_load_dwordx4 v[126:129], v[144:145], off offset:64
	global_load_dwordx4 v[162:165], v[146:147], off offset:64
	global_load_dwordx4 v[166:169], v[148:149], off offset:64
	global_load_dwordx4 v[188:191], v[150:151], off offset:64
	global_load_dwordx4 v[192:195], v[152:153], off offset:64
	global_load_dwordx4 v[196:199], v[154:155], off offset:64
	global_load_dwordx4 v[200:203], v[156:157], off offset:64
	global_load_dwordx4 v[204:207], v[158:159], off offset:64
	v_pk_mul_f32 v[98:99], v[98:99], v[82:83]
	v_pk_mul_f32 v[96:97], v[96:97], v[102:103]
	s_waitcnt vmcnt(0)
;     __device__ __forceinline__ void operator()(const f32x4 (&acc)[2][2][4][2], const pg8::Unit& u, int wr, int wc, int fr, int fq) const {
;     ...
;                 const f32x4 gv = *(const f32x4*)(gate + col) * gscale;
;                 f32x4 lgv = (f32x4){1.f, 1.f, 1.f, 1.f}, lbv = (f32x4){0.f, 0.f, 0.f, 0.f};
;                 if (stats) { lgv = *(const f32x4*)(lg + col); lbv = *(const f32x4*)(lb + col); }
;                 f32x4 xv[2][4];
; #pragma unroll
;                 for (int ai = 0; ai < 2; ++ai)
; #pragma unroll
;                     for (int m = 0; m < 4; ++m) xv[ai][m] = *(const f32x4*)(src + (size_t)(lrow0 + ai * 128 + m * 16) * D + col);
; #pragma unroll
;                 for (int ai = 0; ai < 2; ++ai)
; #pragma unroll
;                     for (int m = 0; m < 4; ++m) {
;                         const size_t off = (size_t)(lrow0 + ai * 128 + m * 16) * D + col;
;                         f32x4 x = xv[ai][m];
;                         if (stats) x = (x - stv[ai][m].x) * stv[ai][m].y * lgv + lbv;
;                         *(f32x4*)(dst + off) = ALPHA * x + gv * acc[ai][bj][m][n];
	v_pk_fma_f32 v[98:99], v[128:129], s[20:21], v[98:99] op_sel_hi:[1,0,1]
	v_pk_fma_f32 v[96:97], v[126:127], s[20:21], v[96:97] op_sel_hi:[1,0,1]
	global_store_dwordx4 v[124:125], v[96:99], off offset:64
	s_nop 1
	v_pk_mul_f32 v[96:97], v[164:165], s[20:21] op_sel_hi:[1,0]
	v_pk_mul_f32 v[98:99], v[162:163], s[20:21] op_sel_hi:[1,0]
	v_pk_fma_f32 v[94:95], v[94:95], v[82:83], v[96:97]
	v_pk_fma_f32 v[92:93], v[92:93], v[102:103], v[98:99]
	global_store_dwordx4 v[120:121], v[92:95], off offset:64
	s_nop 1
	v_pk_mul_f32 v[92:93], v[168:169], s[20:21] op_sel_hi:[1,0]
	v_pk_mul_f32 v[94:95], v[166:167], s[20:21] op_sel_hi:[1,0]
	v_pk_fma_f32 v[90:91], v[90:91], v[82:83], v[92:93]
	v_pk_fma_f32 v[88:89], v[88:89], v[102:103], v[94:95]
	global_store_dwordx4 v[116:117], v[88:91], off offset:64
	s_nop 1
	v_pk_mul_f32 v[88:89], v[190:191], s[20:21] op_sel_hi:[1,0]
	v_pk_mul_f32 v[90:91], v[188:189], s[20:21] op_sel_hi:[1,0]
	v_pk_fma_f32 v[86:87], v[86:87], v[82:83], v[88:89]
	v_pk_fma_f32 v[84:85], v[84:85], v[102:103], v[90:91]
	global_store_dwordx4 v[112:113], v[84:87], off offset:64
	s_nop 1
	v_pk_mul_f32 v[84:85], v[194:195], s[20:21] op_sel_hi:[1,0]
	v_pk_mul_f32 v[86:87], v[192:193], s[20:21] op_sel_hi:[1,0]
	v_pk_fma_f32 v[78:79], v[78:79], v[82:83], v[84:85]
	v_pk_fma_f32 v[76:77], v[76:77], v[102:103], v[86:87]
	global_store_dwordx4 v[108:109], v[76:79], off offset:64
	s_nop 1
	v_pk_mul_f32 v[76:77], v[198:199], s[20:21] op_sel_hi:[1,0]
	v_pk_mul_f32 v[78:79], v[196:197], s[20:21] op_sel_hi:[1,0]
	v_pk_fma_f32 v[74:75], v[74:75], v[82:83], v[76:77]
	v_pk_fma_f32 v[72:73], v[72:73], v[102:103], v[78:79]
	global_store_dwordx4 v[104:105], v[72:75], off offset:64
	s_nop 1
	v_pk_mul_f32 v[72:73], v[202:203], s[20:21] op_sel_hi:[1,0]
	v_pk_mul_f32 v[74:75], v[200:201], s[20:21] op_sel_hi:[1,0]
	v_pk_fma_f32 v[70:71], v[70:71], v[82:83], v[72:73]
	v_pk_fma_f32 v[68:69], v[68:69], v[102:103], v[74:75]
	global_store_dwordx4 v[100:101], v[68:71], off offset:64
	s_nop 1
	v_pk_mul_f32 v[68:69], v[206:207], s[20:21] op_sel_hi:[1,0]
	v_pk_mul_f32 v[70:71], v[204:205], s[20:21] op_sel_hi:[1,0]
	v_pk_fma_f32 v[66:67], v[66:67], v[82:83], v[68:69]
	v_pk_fma_f32 v[64:65], v[64:65], v[102:103], v[70:71]
	global_store_dwordx4 v[80:81], v[64:67], off offset:64
	s_nop 1
	v_or_b32_e32 v64, 0x80, v160
	v_ashrrev_i32_e32 v65, 31, v64
	v_lshl_add_u64 v[64:65], v[64:65], 2, s[22:23]
	s_nop 0
	s_nop 0
	v_pk_mul_f32 v[98:99], v[234:235], 0.5 op_sel_hi:[1,0]
	v_pk_mul_f32 v[102:103], v[232:233], 0.5 op_sel_hi:[1,0]
	global_load_dwordx4 v[64:67], v[144:145], off offset:512
	global_load_dwordx4 v[68:71], v[146:147], off offset:512
	global_load_dwordx4 v[72:75], v[148:149], off offset:512
	global_load_dwordx4 v[76:79], v[150:151], off offset:512
	global_load_dwordx4 v[82:85], v[152:153], off offset:512
	global_load_dwordx4 v[86:89], v[154:155], off offset:512
	global_load_dwordx4 v[90:93], v[156:157], off offset:512
	global_load_dwordx4 v[94:97], v[158:159], off offset:512
	v_pk_mul_f32 v[62:63], v[62:63], v[98:99]
	v_pk_mul_f32 v[60:61], v[60:61], v[102:103]
	s_waitcnt vmcnt(0)
;     __device__ __forceinline__ void operator()(const f32x4 (&acc)[2][2][4][2], const pg8::Unit& u, int wr, int wc, int fr, int fq) const {
;     ...
;                 const f32x4 gv = *(const f32x4*)(gate + col) * gscale;
;                 f32x4 lgv = (f32x4){1.f, 1.f, 1.f, 1.f}, lbv = (f32x4){0.f, 0.f, 0.f, 0.f};
;                 if (stats) { lgv = *(const f32x4*)(lg + col); lbv = *(const f32x4*)(lb + col); }
;                 f32x4 xv[2][4];
; #pragma unroll
;                 for (int ai = 0; ai < 2; ++ai)
; #pragma unroll
;                     for (int m = 0; m < 4; ++m) xv[ai][m] = *(const f32x4*)(src + (size_t)(lrow0 + ai * 128 + m * 16) * D + col);
; #pragma unroll
;                 for (int ai = 0; ai < 2; ++ai)
; #pragma unroll
;                     for (int m = 0; m < 4; ++m) {
;                         const size_t off = (size_t)(lrow0 + ai * 128 + m * 16) * D + col;
;                         f32x4 x = xv[ai][m];
;                         if (stats) x = (x - stv[ai][m].x) * stv[ai][m].y * lgv + lbv;
;                         *(f32x4*)(dst + off) = ALPHA * x + gv * acc[ai][bj][m][n];
;                     }
	v_pk_fma_f32 v[62:63], v[66:67], s[20:21], v[62:63] op_sel_hi:[1,0,1]
	v_pk_fma_f32 v[60:61], v[64:65], s[20:21], v[60:61] op_sel_hi:[1,0,1]
	global_store_dwordx4 v[124:125], v[60:63], off offset:512
	s_nop 1
	v_pk_mul_f32 v[60:61], v[70:71], s[20:21] op_sel_hi:[1,0]
	v_pk_mul_f32 v[62:63], v[68:69], s[20:21] op_sel_hi:[1,0]
	v_pk_fma_f32 v[58:59], v[58:59], v[98:99], v[60:61]
	v_pk_fma_f32 v[56:57], v[56:57], v[102:103], v[62:63]
	global_store_dwordx4 v[120:121], v[56:59], off offset:512
	s_nop 1
	v_pk_mul_f32 v[56:57], v[74:75], s[20:21] op_sel_hi:[1,0]
	v_pk_mul_f32 v[58:59], v[72:73], s[20:21] op_sel_hi:[1,0]
	v_pk_fma_f32 v[54:55], v[54:55], v[98:99], v[56:57]
	v_pk_fma_f32 v[52:53], v[52:53], v[102:103], v[58:59]
	global_store_dwordx4 v[116:117], v[52:55], off offset:512
	s_nop 1
	v_pk_mul_f32 v[52:53], v[78:79], s[20:21] op_sel_hi:[1,0]
	v_pk_mul_f32 v[54:55], v[76:77], s[20:21] op_sel_hi:[1,0]
	v_pk_fma_f32 v[50:51], v[50:51], v[98:99], v[52:53]
	v_pk_fma_f32 v[48:49], v[48:49], v[102:103], v[54:55]
	global_store_dwordx4 v[112:113], v[48:51], off offset:512
	s_nop 1
	v_pk_mul_f32 v[48:49], v[84:85], s[20:21] op_sel_hi:[1,0]
	v_pk_mul_f32 v[50:51], v[82:83], s[20:21] op_sel_hi:[1,0]
	v_pk_fma_f32 v[46:47], v[46:47], v[98:99], v[48:49]
	v_pk_fma_f32 v[44:45], v[44:45], v[102:103], v[50:51]
	global_store_dwordx4 v[108:109], v[44:47], off offset:512
	s_nop 1
	v_pk_mul_f32 v[44:45], v[88:89], s[20:21] op_sel_hi:[1,0]
	v_pk_mul_f32 v[46:47], v[86:87], s[20:21] op_sel_hi:[1,0]
	v_pk_fma_f32 v[42:43], v[42:43], v[98:99], v[44:45]
	v_pk_fma_f32 v[40:41], v[40:41], v[102:103], v[46:47]
	global_store_dwordx4 v[104:105], v[40:43], off offset:512
	s_nop 1
	v_pk_mul_f32 v[40:41], v[92:93], s[20:21] op_sel_hi:[1,0]
	v_pk_mul_f32 v[42:43], v[90:91], s[20:21] op_sel_hi:[1,0]
	v_pk_fma_f32 v[38:39], v[38:39], v[98:99], v[40:41]
	v_pk_fma_f32 v[36:37], v[36:37], v[102:103], v[42:43]
	global_store_dwordx4 v[100:101], v[36:39], off offset:512
	s_nop 1
	v_pk_mul_f32 v[36:37], v[96:97], s[20:21] op_sel_hi:[1,0]
	v_pk_mul_f32 v[38:39], v[94:95], s[20:21] op_sel_hi:[1,0]
	v_pk_fma_f32 v[34:35], v[34:35], v[98:99], v[36:37]
	v_pk_fma_f32 v[32:33], v[32:33], v[102:103], v[38:39]
	global_store_dwordx4 v[80:81], v[32:35], off offset:512
	s_nop 1
	v_or_b32_e32 v32, 0x90, v160
	v_ashrrev_i32_e32 v33, 31, v32
	v_lshl_add_u64 v[32:33], v[32:33], 2, s[22:23]
	s_nop 0
	s_mov_b64 s[22:23], s[0:1]
	s_nop 0
	v_pk_mul_f32 v[64:65], v[238:239], 0.5 op_sel_hi:[1,0]
	v_pk_mul_f32 v[66:67], v[236:237], 0.5 op_sel_hi:[1,0]
	global_load_dwordx4 v[32:35], v[144:145], off offset:576
	global_load_dwordx4 v[36:39], v[146:147], off offset:576
	global_load_dwordx4 v[40:43], v[148:149], off offset:576
	global_load_dwordx4 v[44:47], v[150:151], off offset:576
	global_load_dwordx4 v[48:51], v[152:153], off offset:576
	global_load_dwordx4 v[52:55], v[154:155], off offset:576
	global_load_dwordx4 v[56:59], v[156:157], off offset:576
	global_load_dwordx4 v[60:63], v[158:159], off offset:576
	v_pk_mul_f32 v[30:31], v[30:31], v[64:65]
	v_pk_mul_f32 v[28:29], v[28:29], v[66:67]
	s_waitcnt vmcnt(0)
	v_pk_fma_f32 v[30:31], v[34:35], s[20:21], v[30:31] op_sel_hi:[1,0,1]
	v_pk_fma_f32 v[28:29], v[32:33], s[20:21], v[28:29] op_sel_hi:[1,0,1]
	global_store_dwordx4 v[124:125], v[28:31], off offset:576
	s_nop 1
	v_pk_mul_f32 v[28:29], v[38:39], s[20:21] op_sel_hi:[1,0]
	v_pk_mul_f32 v[30:31], v[36:37], s[20:21] op_sel_hi:[1,0]
	v_pk_fma_f32 v[26:27], v[26:27], v[64:65], v[28:29]
	v_pk_fma_f32 v[24:25], v[24:25], v[66:67], v[30:31]
	global_store_dwordx4 v[120:121], v[24:27], off offset:576
	s_nop 1
	v_pk_mul_f32 v[24:25], v[42:43], s[20:21] op_sel_hi:[1,0]
	v_pk_mul_f32 v[26:27], v[40:41], s[20:21] op_sel_hi:[1,0]
	v_pk_fma_f32 v[22:23], v[22:23], v[64:65], v[24:25]
	v_pk_fma_f32 v[20:21], v[20:21], v[66:67], v[26:27]
	global_store_dwordx4 v[116:117], v[20:23], off offset:576
	s_nop 1
	v_pk_mul_f32 v[20:21], v[46:47], s[20:21] op_sel_hi:[1,0]
	v_pk_mul_f32 v[22:23], v[44:45], s[20:21] op_sel_hi:[1,0]
	v_pk_fma_f32 v[18:19], v[18:19], v[64:65], v[20:21]
	v_pk_fma_f32 v[16:17], v[16:17], v[66:67], v[22:23]
	global_store_dwordx4 v[112:113], v[16:19], off offset:576
	s_nop 1
	v_pk_mul_f32 v[16:17], v[50:51], s[20:21] op_sel_hi:[1,0]
	v_pk_mul_f32 v[18:19], v[48:49], s[20:21] op_sel_hi:[1,0]
	v_pk_fma_f32 v[14:15], v[14:15], v[64:65], v[16:17]
	v_pk_fma_f32 v[12:13], v[12:13], v[66:67], v[18:19]
	global_store_dwordx4 v[108:109], v[12:15], off offset:576
	s_nop 1
	v_pk_mul_f32 v[12:13], v[54:55], s[20:21] op_sel_hi:[1,0]
	v_pk_mul_f32 v[14:15], v[52:53], s[20:21] op_sel_hi:[1,0]
	v_pk_fma_f32 v[10:11], v[10:11], v[64:65], v[12:13]
	v_pk_fma_f32 v[8:9], v[8:9], v[66:67], v[14:15]
	global_store_dwordx4 v[104:105], v[8:11], off offset:576
	s_nop 1
	v_pk_mul_f32 v[8:9], v[58:59], s[20:21] op_sel_hi:[1,0]
	v_pk_mul_f32 v[10:11], v[56:57], s[20:21] op_sel_hi:[1,0]
	v_pk_fma_f32 v[6:7], v[6:7], v[64:65], v[8:9]
	v_pk_fma_f32 v[4:5], v[4:5], v[66:67], v[10:11]
	global_store_dwordx4 v[100:101], v[4:7], off offset:576
	s_nop 1
	v_pk_mul_f32 v[4:5], v[62:63], s[20:21] op_sel_hi:[1,0]
	v_pk_mul_f32 v[6:7], v[60:61], s[20:21] op_sel_hi:[1,0]
	v_pk_fma_f32 v[2:3], v[2:3], v[64:65], v[4:5]
	v_pk_fma_f32 v[0:1], v[0:1], v[66:67], v[6:7]
	global_store_dwordx4 v[80:81], v[0:3], off offset:576
	s_cbranch_vccnz .LBB0_302
